# mix_pass_a: row-invariant loads hoisted out of the row loop, all per-row loads up front behind one wait
# baseline (speedup 1.0000x reference)
.LBB0_1183:
	s_and_b64 vcc, exec, s[6:7]
	s_cbranch_vccz .LBB0_2071
	v_readlane_b32 s2, v253, 4
	v_mbcnt_lo_u32_b32 v0, -1, 0
	v_mbcnt_hi_u32_b32 v0, -1, v0
	v_readlane_b32 s4, v253, 8
	s_mov_b64 s[20:21], 0x400
	v_add_u32_e32 v2, s2, v0
	s_nop 0
	v_readfirstlane_b32 s3, v2
	s_ashr_i32 s2, s3, 6
	s_add_i32 s12, s2, s4
	s_cmpk_gt_i32 s12, 0x23ff
	s_cbranch_scc1 .LBB0_1305
	s_load_dwordx2 s[8:9], s[0:1], 0x1b0
	s_load_dwordx4 s[4:7], s[0:1], 0x110
	s_load_dwordx2 s[10:11], s[0:1], 0xb8
	v_readlane_b32 s14, v253, 13
	v_readlane_b32 s15, v253, 14
	s_mov_b32 s17, s15
	s_waitcnt lgkmcnt(0)
	s_add_u32 s40, s8, 0x33400000
	s_addc_u32 s41, s9, 0
	s_lshl_b32 s16, s90, 10
	s_lshl_b64 s[14:15], s[16:17], 2
	s_add_u32 s18, s6, s14
	s_addc_u32 s19, s7, s15
	s_lshl_b32 s16, s90, 12
	s_lshl_b64 s[6:7], s[16:17], 2
	v_and_b32_e32 v3, 63, v0
	s_add_u32 s4, s4, s6
	s_addc_u32 s5, s5, s7
	v_lshlrev_b32_e32 v48, 4, v3
	v_mov_b32_e32 v49, v1
	s_waitcnt vmcnt(0)
	v_lshl_add_u64 v[52:53], s[4:5], 0, v[48:49]
	s_mov_b64 s[4:5], 0x1000
	v_lshl_add_u64 v[54:55], v[52:53], 0, s[4:5]
	s_mov_b64 s[4:5], 0x2000
	v_lshl_add_u64 v[56:57], v[52:53], 0, s[4:5]
	s_mov_b64 s[4:5], 0x3000
	v_lshl_add_u64 v[58:59], v[52:53], 0, s[4:5]
	s_mov_b64 s[4:5], 0x1400
	v_lshl_add_u64 v[62:63], v[52:53], 0, s[4:5]
	s_mov_b64 s[4:5], 0x2400
	s_mul_i32 s16, s90, 0xd20
	v_lshl_add_u64 v[64:65], v[52:53], 0, s[4:5]
	s_mov_b64 s[4:5], 0x3400
	s_lshl_b64 s[6:7], s[16:17], 2
	v_lshl_add_u64 v[66:67], v[52:53], 0, s[4:5]
	s_mov_b64 s[4:5], 0x800
	s_add_u32 s10, s10, s6
	v_or_b32_e32 v28, 0xc00, v3
	v_lshl_add_u64 v[68:69], v[52:53], 0, s[4:5]
	s_mov_b64 s[4:5], 0x1800
	s_addc_u32 s11, s11, s7
	v_lshlrev_b32_e32 v0, 2, v28
	v_or_b32_e32 v32, 0xc40, v3
	v_lshl_add_u64 v[70:71], v[52:53], 0, s[4:5]
	s_mov_b64 s[4:5], 0x2800
	v_lshl_add_u64 v[30:31], s[10:11], 0, v[0:1]
	v_lshlrev_b32_e32 v0, 2, v32
	v_or_b32_e32 v36, 0xc80, v3
	v_lshl_add_u64 v[72:73], v[52:53], 0, s[4:5]
	s_mov_b64 s[4:5], 0x3800
	v_lshl_add_u64 v[34:35], s[10:11], 0, v[0:1]
	v_lshlrev_b32_e32 v0, 2, v36
	v_or_b32_e32 v40, 0xcc0, v3
	v_lshl_add_u64 v[74:75], v[52:53], 0, s[4:5]
	s_mov_b64 s[4:5], 0xc00
	v_lshl_add_u64 v[38:39], s[10:11], 0, v[0:1]
	v_lshlrev_b32_e32 v0, 2, v40
	v_or_b32_e32 v44, 0xd00, v3
	v_lshl_add_u64 v[76:77], v[52:53], 0, s[4:5]
	s_mov_b64 s[4:5], 0x1c00
	v_lshl_add_u64 v[42:43], s[10:11], 0, v[0:1]
	v_lshlrev_b32_e32 v0, 2, v44
	v_lshl_add_u64 v[78:79], v[52:53], 0, s[4:5]
	s_mov_b64 s[4:5], 0x2c00
	s_mov_b32 s7, s17
	v_lshl_add_u64 v[46:47], s[10:11], 0, v[0:1]
	v_lshl_add_u64 v[80:81], v[52:53], 0, s[4:5]
	s_mov_b64 s[4:5], 0x3c00
	v_lshlrev_b32_e32 v0, 1, v3
	v_writelane_b32 v253, s6, 13
	v_lshl_add_u64 v[82:83], v[52:53], 0, s[4:5]
	v_lshl_add_u64 v[8:9], s[8:9], 0, v[0:1]
	s_mov_b64 s[4:5], 0x3fa00000
	v_lshlrev_b32_e32 v0, 3, v3
	v_writelane_b32 v253, s7, 14
	s_mov_b32 s91, s17
	s_bfe_u32 s42, s3, 0x30006
	v_lshl_add_u64 v[84:85], v[8:9], 0, s[4:5]
	v_lshl_add_u64 v[8:9], s[8:9], 0, v[0:1]
	s_mov_b64 s[4:5], 0x400c0000
	s_lshl_b64 s[14:15], s[90:91], 7
	s_lshl_b64 s[16:17], s[90:91], 2
	s_add_i32 s43, s42, 1
	s_add_i32 s44, s42, 2
	v_lshl_add_u64 v[86:87], v[8:9], 0, s[4:5]
	s_ashr_i32 s3, s2, 31
	v_readlane_b32 s4, v253, 8
	s_add_u32 s2, s4, s2
	v_readlane_b32 s4, v253, 47
	s_addc_u32 s3, s4, s3
	s_mulk_i32 s3, 0x5800
	s_mul_hi_u32 s4, s2, 0x5800
	s_add_i32 s4, s4, s3
	s_mulk_i32 s2, 0x5800
	v_lshlrev_b32_e32 v26, 2, v3
	s_add_u32 s2, s40, s2
	v_or_b32_e32 v2, 0x100, v26
	v_or_b32_e32 v4, 0x200, v26
	v_or_b32_e32 v6, 0x300, v26
	s_addc_u32 s3, s41, s4
	v_cmp_gt_u32_e64 s[6:7], 32, v3
	v_lshl_add_u64 v[50:51], s[18:19], 0, v[48:49]
	v_lshl_add_u64 v[60:61], v[52:53], 0, s[20:21]
	v_lshl_add_u64 v[88:89], s[2:3], 0, v[48:49]
	v_or_b32_e32 v27, 0xffffff00, v26
	v_lshlrev_b32_e32 v90, 2, v2
	v_lshlrev_b32_e32 v92, 2, v4
	v_lshlrev_b32_e32 v94, 2, v6
	global_load_dword v98, v[30:31], off
	global_load_dword v99, v[34:35], off
	global_load_dword v100, v[38:39], off
	global_load_dword v101, v[42:43], off
	s_and_saveexec_b64 s[30:31], s[6:7]
	global_load_dword v102, v[46:47], off
	s_or_b64 exec, exec, s[30:31]
	global_load_dwordx4 v[106:109], v[50:51], off
	global_load_dwordx4 v[110:113], v[50:51], off offset:1024
	global_load_dwordx4 v[114:117], v[50:51], off offset:2048
	global_load_dwordx4 v[118:121], v[50:51], off offset:3072
	global_load_dwordx4 v[130:133], v[52:53], off
	global_load_dwordx4 v[134:137], v[60:61], off
	global_load_dwordx4 v[138:141], v[68:69], off
	global_load_dwordx4 v[142:145], v[76:77], off
	global_load_dwordx4 v[146:149], v[54:55], off
	global_load_dwordx4 v[150:153], v[62:63], off
	global_load_dwordx4 v[154:157], v[70:71], off
	global_load_dwordx4 v[158:161], v[78:79], off
	global_load_dwordx4 v[162:165], v[56:57], off
	global_load_dwordx4 v[166:169], v[64:65], off
	global_load_dwordx4 v[174:177], v[72:73], off
	global_load_dwordx4 v[178:181], v[80:81], off
	global_load_dwordx4 v[182:185], v[58:59], off
	global_load_dwordx4 v[186:189], v[66:67], off
	global_load_dwordx4 v[190:193], v[74:75], off
	global_load_dwordx4 v[194:197], v[82:83], off
	s_branch .LBB0_1188

.LBB0_1193:
	s_add_u32 s49, s14, s2
	s_addc_u32 s52, s15, 0
	s_mul_i32 s2, s52, 3
	s_mul_hi_u32 s3, s49, 3
	s_add_i32 s46, s3, s2
	s_mul_i32 s48, s49, 3
	s_ashr_i32 s13, s12, 31
	v_lshlrev_b32_e32 v0, 2, v26
	s_add_u32 s34, s26, 0x3480
	s_addc_u32 s35, s27, 0
	s_cmp_eq_u64 s[10:11], 0
	s_cbranch_scc1 .Lpa_nozp
	v_lshlrev_b32_e32 v96, 2, v28
	global_load_dword v122, v96, s[26:27]
	global_load_dword v127, v96, s[10:11]
	v_lshlrev_b32_e32 v96, 2, v32
	global_load_dword v123, v96, s[26:27]
	global_load_dword v103, v96, s[10:11]
	v_lshlrev_b32_e32 v96, 2, v36
	global_load_dword v124, v96, s[26:27]
	global_load_dword v104, v96, s[10:11]
	v_lshlrev_b32_e32 v96, 2, v40
	global_load_dword v125, v96, s[26:27]
	global_load_dword v29, v96, s[10:11]
	s_and_saveexec_b64 s[30:31], s[6:7]
	v_lshlrev_b32_e32 v96, 2, v44
	global_load_dword v126, v96, s[26:27]
	global_load_dword v33, v96, s[10:11]
	s_or_b64 exec, exec, s[30:31]
	s_branch .Lpa_p1done
.Lpa_nozp:
	v_lshlrev_b32_e32 v96, 2, v28
	global_load_dword v122, v96, s[26:27]
	v_mov_b32_e32 v127, 0
	v_lshlrev_b32_e32 v96, 2, v32
	global_load_dword v123, v96, s[26:27]
	v_mov_b32_e32 v103, 0
	v_lshlrev_b32_e32 v96, 2, v36
	global_load_dword v124, v96, s[26:27]
	v_mov_b32_e32 v104, 0
	v_lshlrev_b32_e32 v96, 2, v40
	global_load_dword v125, v96, s[26:27]
	v_mov_b32_e32 v29, 0
	s_and_saveexec_b64 s[30:31], s[6:7]
	v_lshlrev_b32_e32 v96, 2, v44
	global_load_dword v126, v96, s[26:27]
	s_or_b64 exec, exec, s[30:31]
	v_mov_b32_e32 v33, 0
.Lpa_p1done:
	global_load_dwordx4 v[10:13], v0, s[34:35]
	global_load_dwordx4 v[14:17], v0, s[34:35] offset:1024
	global_load_dwordx4 v[18:21], v0, s[34:35] offset:2048
	global_load_dwordx4 v[22:25], v0, s[34:35] offset:3072
	s_cmp_lt_u32 s45, 3
	s_cbranch_scc1 .Lpa_t0_early
	s_add_u32 s8, s26, 0xffff2c80
	s_addc_u32 s9, s27, -1
.Lpa_t0_ld:
	global_load_dwordx4 v[218:221], v0, s[8:9]
	global_load_dwordx4 v[222:225], v0, s[8:9] offset:1024
	global_load_dwordx4 v[226:229], v0, s[8:9] offset:2048
	global_load_dwordx4 v[230:233], v0, s[8:9] offset:3072
	s_branch .Lpa_t0_done
.Lpa_t0_early:
	s_and_b64 vcc, exec, s[22:23]
	s_cbranch_vccz .Lpa_t0_zero
	s_load_dwordx2 s[2:3], s[0:1], 0x28
	s_add_u32 s4, s48, s42
	s_addc_u32 s5, s46, 0
	s_lshl_b64 s[4:5], s[4:5], 12
	s_waitcnt lgkmcnt(0)
	s_add_u32 s8, s2, s4
	s_addc_u32 s9, s3, s5
	s_branch .Lpa_t0_ld
.Lpa_t0_zero:
	v_mov_b32_e32 v218, 0
	v_mov_b32_e32 v219, 0
	v_mov_b32_e32 v220, 0
	v_mov_b32_e32 v221, 0
	v_mov_b32_e32 v222, 0
	v_mov_b32_e32 v223, 0
	v_mov_b32_e32 v224, 0
	v_mov_b32_e32 v225, 0
	v_mov_b32_e32 v226, 0
	v_mov_b32_e32 v227, 0
	v_mov_b32_e32 v228, 0
	v_mov_b32_e32 v229, 0
	v_mov_b32_e32 v230, 0
	v_mov_b32_e32 v231, 0
	v_mov_b32_e32 v232, 0
	v_mov_b32_e32 v233, 0
.Lpa_t0_done:
	s_cmp_lt_u32 s45, 2
	s_cbranch_scc1 .Lpa_t1_early
	s_add_u32 s8, s26, 0xffff8480
	s_addc_u32 s9, s27, -1
.Lpa_t1_ld:
	global_load_dwordx4 v[234:237], v0, s[8:9]
	global_load_dwordx4 v[238:241], v0, s[8:9] offset:1024
	global_load_dwordx4 v[242:245], v0, s[8:9] offset:2048
	global_load_dwordx4 v[246:249], v0, s[8:9] offset:3072
	s_branch .Lpa_t1_done
.Lpa_t1_early:
	s_and_b64 vcc, exec, s[22:23]
	s_cbranch_vccz .Lpa_t1_zero
	s_load_dwordx2 s[2:3], s[0:1], 0x28
	s_add_u32 s4, s48, s43
	s_addc_u32 s5, s46, 0
	s_lshl_b64 s[4:5], s[4:5], 12
	s_waitcnt lgkmcnt(0)
	s_add_u32 s8, s2, s4
	s_addc_u32 s9, s3, s5
	s_branch .Lpa_t1_ld
.Lpa_t1_zero:
	v_mov_b32_e32 v234, 0
	v_mov_b32_e32 v235, 0
	v_mov_b32_e32 v236, 0
	v_mov_b32_e32 v237, 0
	v_mov_b32_e32 v238, 0
	v_mov_b32_e32 v239, 0
	v_mov_b32_e32 v240, 0
	v_mov_b32_e32 v241, 0
	v_mov_b32_e32 v242, 0
	v_mov_b32_e32 v243, 0
	v_mov_b32_e32 v244, 0
	v_mov_b32_e32 v245, 0
	v_mov_b32_e32 v246, 0
	v_mov_b32_e32 v247, 0
	v_mov_b32_e32 v248, 0
	v_mov_b32_e32 v249, 0
.Lpa_t1_done:
	s_cmp_lt_u32 s45, 1
	s_cbranch_scc1 .Lpa_t2_early
	s_add_u32 s8, s26, 0xffffdc80
	s_addc_u32 s9, s27, -1
.Lpa_t2_ld:
	global_load_dwordx4 v[206:209], v0, s[8:9]
	global_load_dwordx4 v[198:201], v0, s[8:9] offset:1024
	global_load_dwordx4 v[2:5], v0, s[8:9] offset:2048
	global_load_dwordx4 v[6:9], v0, s[8:9] offset:3072
	s_branch .Lpa_t2_done
.Lpa_t2_early:
	s_and_b64 vcc, exec, s[22:23]
	s_cbranch_vccz .Lpa_t2_zero
	s_load_dwordx2 s[2:3], s[0:1], 0x28
	s_add_u32 s4, s48, s44
	s_addc_u32 s5, s46, 0
	s_lshl_b64 s[4:5], s[4:5], 12
	s_waitcnt lgkmcnt(0)
	s_add_u32 s8, s2, s4
	s_addc_u32 s9, s3, s5
	s_branch .Lpa_t2_ld
.Lpa_t2_zero:
	v_mov_b32_e32 v206, 0
	v_mov_b32_e32 v207, 0
	v_mov_b32_e32 v208, 0
	v_mov_b32_e32 v209, 0
	v_mov_b32_e32 v198, 0
	v_mov_b32_e32 v199, 0
	v_mov_b32_e32 v200, 0
	v_mov_b32_e32 v201, 0
	v_mov_b32_e32 v2, 0
	v_mov_b32_e32 v3, 0
	v_mov_b32_e32 v4, 0
	v_mov_b32_e32 v5, 0
	v_mov_b32_e32 v6, 0
	v_mov_b32_e32 v7, 0
	v_mov_b32_e32 v8, 0
	v_mov_b32_e32 v9, 0
.Lpa_t2_done:
	v_mov_b32_e32 v96, 0x300
	v_mad_i64_i32 v[214:215], s[4:5], s12, v96, v[84:85]
	s_lshl_b64 s[8:9], s[12:13], 11
	v_lshl_add_u64 v[96:97], v[86:87], 0, s[8:9]
	s_waitcnt vmcnt(0)
	v_sub_f32_e32 v127, v127, v122
	v_fmac_f32_e32 v122, v127, v98
	v_add_f32_e32 v122, v122, v122
	v_mul_f32_e32 v122, 0x3fb8aa3b, v122
	v_exp_f32_e32 v122, v122
	s_nop 0
	v_add_f32_e32 v122, 1.0, v122
	v_rcp_f32_e32 v217, v122
	s_nop 0
	v_fma_f32 v122, v217, -2.0, 1.0
	v_bfe_u32 v217, v122, 16, 1
	v_add3_u32 v122, v122, v217, s85
	global_store_short_d16_hi v[214:215], v122, off
	v_sub_f32_e32 v103, v103, v123
	v_fmac_f32_e32 v123, v103, v99
	v_bfe_u32 v217, v123, 16, 1
	v_add3_u32 v123, v123, v217, s85
	global_store_short_d16_hi v[214:215], v123, off offset:128
	v_sub_f32_e32 v104, v104, v124
	v_fmac_f32_e32 v124, v104, v100
	v_mul_f32_e32 v124, 0xbfb8aa3b, v124
	v_exp_f32_e32 v124, v124
	s_nop 0
	v_add_f32_e32 v124, 1.0, v124
	v_rcp_f32_e32 v124, v124
	s_nop 0
	v_bfe_u32 v217, v124, 16, 1
	v_add3_u32 v124, v124, v217, s85
	global_store_short_d16_hi v[214:215], v124, off offset:256
	v_sub_f32_e32 v29, v29, v125
	v_fmac_f32_e32 v125, v29, v101
	v_mul_f32_e32 v125, 0xbfb8aa3b, v125
	v_exp_f32_e32 v125, v125
	s_nop 0
	v_add_f32_e32 v125, 1.0, v125
	v_rcp_f32_e32 v125, v125
	s_nop 0
	v_bfe_u32 v217, v125, 16, 1
	v_add3_u32 v125, v125, v217, s85
	global_store_short_d16_hi v[214:215], v125, off offset:384
	v_sub_f32_e32 v33, v33, v126
	v_fmac_f32_e32 v126, v33, v102
	v_mul_f32_e32 v126, 0xbfb8aa3b, v126
	v_exp_f32_e32 v126, v126
	s_nop 0
	v_add_f32_e32 v126, 1.0, v126
	v_rcp_f32_e32 v126, v126
	s_nop 0
	v_cndmask_b32_e64 v126, 0, v126, s[6:7]
	v_bfe_u32 v217, v126, 16, 1
	v_add3_u32 v126, v126, v217, s85
	global_store_short_d16_hi v[214:215], v126, off offset:512
	global_store_short v[214:215], v1, off offset:640
	v_pk_fma_f32 v[170:171], v[220:221], v[132:133], v[108:109]
	v_pk_fma_f32 v[204:205], v[218:219], v[130:131], v[106:107]
	v_pk_fma_f32 v[170:171], v[236:237], v[148:149], v[170:171]
	v_pk_fma_f32 v[204:205], v[234:235], v[146:147], v[204:205]
	v_pk_fma_f32 v[170:171], v[208:209], v[164:165], v[170:171]
	v_pk_fma_f32 v[204:205], v[206:207], v[162:163], v[204:205]
	v_pk_fma_f32 v[204:205], v[10:11], v[182:183], v[204:205]
	v_pk_fma_f32 v[170:171], v[12:13], v[184:185], v[170:171]
	v_bfe_u32 v217, v204, 16, 1
	v_add3_u32 v204, v204, v217, s85
	v_bfe_u32 v217, v205, 16, 1
	v_lshrrev_b32_e32 v204, 16, v204
	v_add3_u32 v205, v205, v217, s85
	v_and_or_b32 v204, v205, s84, v204
	v_bfe_u32 v205, v170, 16, 1
	v_add3_u32 v205, v170, v205, s85
	v_bfe_u32 v170, v171, 16, 1
	v_lshrrev_b32_e32 v205, 16, v205
	v_add3_u32 v170, v171, v170, s85
	v_and_or_b32 v205, v170, s84, v205
	global_store_dwordx2 v[96:97], v[204:205], off
	v_pk_fma_f32 v[170:171], v[224:225], v[136:137], v[112:113]
	v_pk_fma_f32 v[204:205], v[222:223], v[134:135], v[110:111]
	v_pk_fma_f32 v[170:171], v[240:241], v[152:153], v[170:171]
	v_pk_fma_f32 v[204:205], v[238:239], v[150:151], v[204:205]
	v_pk_fma_f32 v[170:171], v[200:201], v[168:169], v[170:171]
	v_pk_fma_f32 v[204:205], v[198:199], v[166:167], v[204:205]
	v_pk_fma_f32 v[204:205], v[14:15], v[186:187], v[204:205]
	v_pk_fma_f32 v[170:171], v[16:17], v[188:189], v[170:171]
	v_bfe_u32 v217, v204, 16, 1
	v_add3_u32 v204, v204, v217, s85
	v_bfe_u32 v217, v205, 16, 1
	v_lshrrev_b32_e32 v204, 16, v204
	v_add3_u32 v205, v205, v217, s85
	v_and_or_b32 v204, v205, s84, v204
	v_bfe_u32 v205, v170, 16, 1
	v_add3_u32 v205, v170, v205, s85
	v_bfe_u32 v170, v171, 16, 1
	v_lshrrev_b32_e32 v205, 16, v205
	v_add3_u32 v170, v171, v170, s85
	v_and_or_b32 v205, v170, s84, v205
	global_store_dwordx2 v[96:97], v[204:205], off offset:512
	v_pk_fma_f32 v[170:171], v[228:229], v[140:141], v[116:117]
	v_pk_fma_f32 v[204:205], v[226:227], v[138:139], v[114:115]
	v_pk_fma_f32 v[170:171], v[244:245], v[156:157], v[170:171]
	v_pk_fma_f32 v[204:205], v[242:243], v[154:155], v[204:205]
	v_pk_fma_f32 v[170:171], v[4:5], v[176:177], v[170:171]
	v_pk_fma_f32 v[204:205], v[2:3], v[174:175], v[204:205]
	v_pk_fma_f32 v[204:205], v[18:19], v[190:191], v[204:205]
	v_pk_fma_f32 v[170:171], v[20:21], v[192:193], v[170:171]
	v_bfe_u32 v217, v204, 16, 1
	v_add3_u32 v204, v204, v217, s85
	v_bfe_u32 v217, v205, 16, 1
	v_lshrrev_b32_e32 v204, 16, v204
	v_add3_u32 v205, v205, v217, s85
	v_and_or_b32 v204, v205, s84, v204
	v_bfe_u32 v205, v170, 16, 1
	v_add3_u32 v205, v170, v205, s85
	v_bfe_u32 v170, v171, 16, 1
	v_lshrrev_b32_e32 v205, 16, v205
	v_add3_u32 v170, v171, v170, s85
	v_and_or_b32 v205, v170, s84, v205
	global_store_dwordx2 v[96:97], v[204:205], off offset:1024
	v_pk_fma_f32 v[170:171], v[232:233], v[144:145], v[120:121]
	v_pk_fma_f32 v[204:205], v[230:231], v[142:143], v[118:119]
	v_pk_fma_f32 v[170:171], v[248:249], v[160:161], v[170:171]
	v_pk_fma_f32 v[204:205], v[246:247], v[158:159], v[204:205]
	v_pk_fma_f32 v[170:171], v[8:9], v[180:181], v[170:171]
	v_pk_fma_f32 v[204:205], v[6:7], v[178:179], v[204:205]
	v_pk_fma_f32 v[204:205], v[22:23], v[194:195], v[204:205]
	v_pk_fma_f32 v[170:171], v[24:25], v[196:197], v[170:171]
	v_bfe_u32 v217, v204, 16, 1
	v_add3_u32 v204, v204, v217, s85
	v_bfe_u32 v217, v205, 16, 1
	v_lshrrev_b32_e32 v204, 16, v204
	v_add3_u32 v205, v205, v217, s85
	v_and_or_b32 v204, v205, s84, v204
	v_bfe_u32 v205, v170, 16, 1
	v_add3_u32 v205, v170, v205, s85
	v_bfe_u32 v170, v171, 16, 1
	v_lshrrev_b32_e32 v205, 16, v205
	v_add3_u32 v170, v171, v170, s85
	v_and_or_b32 v205, v170, s84, v205
	global_store_dwordx2 v[96:97], v[204:205], off offset:1536
	s_ashr_i32 s2, s12, 11
	s_and_b64 s[4:5], s[22:23], exec
	s_cselect_b32 s3, 8, 0x800
	s_add_i32 s4, s3, -1
	s_mov_b64 s[18:19], 0x400
	s_cmp_lg_u32 s45, s4
	s_cbranch_scc1 .LBB0_1302
	s_ashr_i32 s8, s2, 31
	s_add_u32 s10, s16, s2
	s_load_dwordx2 s[4:5], s[0:1], 0x1a8
	s_addc_u32 s11, s17, s8
	s_and_b64 s[8:9], s[22:23], exec
	s_cselect_b32 s8, s49, s10
	s_cselect_b32 s9, s52, s11
	s_mulk_i32 s9, 0x3480
	s_mul_hi_u32 s10, s8, 0x3480
	s_add_i32 s10, s10, s9
	s_waitcnt lgkmcnt(0)
	v_lshl_add_u64 v[2:3], s[4:5], 0, v[48:49]
	s_and_b64 s[4:5], s[22:23], exec
	s_mov_b32 s4, 0x8aba400
	s_mulk_i32 s8, 0x3480
	s_cselect_b32 s4, s4, 0x4a00000
	s_add_u32 s4, s8, s4
	s_addc_u32 s5, s10, 0
	v_lshl_add_u64 v[2:3], v[2:3], 0, s[4:5]
	s_mov_b64 s[8:9], 0
	v_mov_b32_e32 v6, v27
	v_mov_b64_e32 v[4:5], v[88:89]
